# combo12 but sample chunk-head first only on odd workgroups (odd XCDs), last on even ones
# baseline (speedup 1.0000x reference)
; #define LAS __attribute__((address_space(3)))
; __device__ __forceinline__ void dn_prep(const Params& p, LAS unsigned char* lds) {
;     const int tid = threadIdx.x, lane = tid & 63, wid = tid >> 6, fr = lane & 15, fq = lane >> 4;
;     LAS bf16_t* Qs = (LAS bf16_t*)(lds + L_QS); LAS bf16_t* Ks = (LAS bf16_t*)(lds + L_KS); LAS bf16_t* Kts = (LAS bf16_t*)(lds + L_KT); LAS bf16_t* Vts = (LAS bf16_t*)(lds + L_VT);
;     LAS float* As = (LAS float*)(lds + L_AS); LAS bf16_t* Tu = (LAS bf16_t*)(lds + L_TU); LAS bf16_t* Tw = (LAS bf16_t*)(lds + L_TW);
;     LAS float* beta_s = (LAS float*)(lds + L_BG); LAS float* G_s = beta_s + 64;
;     const bf16_t* Z = (const bf16_t*)(p.ws + WS_Z);
;     const float* BA = (const float*)(p.ws + WS_BA);
;     unsigned char* dn = (unsigned char*)p.out;
;     LAS float* cw_s = (LAS float*)(lds + 108032);
;     int hb = -1;
;     for (int ci = blockIdx.x; ci < NCH; ci += gridDim.x) {
;     ...
;             for (int i = 1; i < 64; ++i) {
; #pragma unroll
;                 for (int j4 = 8; j4 < (i + 3) / 4; ++j4) rhi[j4 - 8] = *(const LAS f32x4*)(Asz + i * 68 + j4 * 4);
;                 if (i + 1 < 64) {
; #pragma unroll
;                     for (int j4 = 0; j4 < ((i + 4) / 4 < 8 ? (i + 4) / 4 : 8); ++j4) rlo[(i + 1) & 1][j4] = *(const LAS f32x4*)(Asz + (i + 1) * 68 + j4 * 4);
;                 }
;                 float a0 = (lane == i) ? 1.f : 0.f, a1 = 0.f, a2 = 0.f, a3 = 0.f;
.LBB0_187:
	s_cmp_lt_i32 s84, 3
	s_cselect_b64 s[4:5], -1, 0
	s_and_b64 s[0:1], s[4:5], s[2:3]
	s_andn2_b64 vcc, exec, s[0:1]
	s_cbranch_vccnz .LBB0_385
	s_cmpk_gt_i32 s33, 0x47f
	s_cbranch_scc1 .LBB0_385
	v_and_b32_e32 v152, 63, v184
	v_cmp_eq_u32_e32 vcc, 1, v152
	s_add_u32 s0, s50, 0xbc40000
	v_writelane_b32 v248, s4, 6
	v_cndmask_b32_e64 v160, 0, 1.0, vcc
	v_cmp_eq_u32_e32 vcc, 2, v152
	s_addc_u32 s1, s51, 0
	v_writelane_b32 v248, s5, 7
	v_cndmask_b32_e64 v161, 0, 1.0, vcc
	v_cmp_eq_u32_e32 vcc, 3, v152
	s_add_u32 s14, s48, 0x1200000
	v_writelane_b32 v248, s0, 8
	v_cndmask_b32_e64 v162, 0, 1.0, vcc
	v_cmp_eq_u32_e32 vcc, 4, v152
	s_addc_u32 s34, s49, 0
	v_writelane_b32 v248, s1, 9
	v_cndmask_b32_e64 v163, 0, 1.0, vcc
	v_cmp_eq_u32_e32 vcc, 5, v152
	s_add_u32 s0, s48, 0x2400000
	v_writelane_b32 v248, s0, 10
	v_cndmask_b32_e64 v164, 0, 1.0, vcc
	v_cmp_eq_u32_e32 vcc, 6, v152
	s_addc_u32 s0, s49, 0
	s_add_u32 s39, s48, 0x3600000
	v_cndmask_b32_e64 v165, 0, 1.0, vcc
	v_cmp_eq_u32_e32 vcc, 7, v152
	v_writelane_b32 v248, s0, 11
	s_addc_u32 s36, s49, 0
	v_cndmask_b32_e64 v166, 0, 1.0, vcc
	v_cmp_eq_u32_e32 vcc, 8, v152
	s_add_i32 s0, 0, 0x1a400
	v_lshlrev_b32_e32 v0, 2, v152
	v_cndmask_b32_e64 v167, 0, 1.0, vcc
	v_cmp_eq_u32_e32 vcc, 9, v152
	v_add_u32_e32 v153, s0, v0
	s_movk_i32 s0, 0xff
	v_cndmask_b32_e64 v168, 0, 1.0, vcc
	v_cmp_eq_u32_e32 vcc, 10, v152
	v_cmp_lt_u32_e64 s[4:5], s0, v184
	v_cmp_eq_u32_e64 s[0:1], 0, v152
	v_cndmask_b32_e64 v169, 0, 1.0, vcc
	v_cmp_eq_u32_e32 vcc, 11, v152
	v_writelane_b32 v248, s0, 12
	v_lshrrev_b32_e32 v1, 6, v184
	v_cndmask_b32_e64 v170, 0, 1.0, vcc
	v_cmp_eq_u32_e32 vcc, 12, v152
	v_writelane_b32 v248, s1, 13
	v_cndmask_b32_e64 v157, 0, 1.0, s[0:1]
	v_cndmask_b32_e64 v171, 0, 1.0, vcc
	v_cmp_eq_u32_e32 vcc, 13, v152
	v_cmp_gt_u32_e64 s[0:1], 2, v152
	v_bfe_u32 v3, v184, 6, 2
	v_cndmask_b32_e64 v172, 0, 1.0, vcc
	v_cmp_eq_u32_e32 vcc, 14, v152
	v_writelane_b32 v248, s0, 14
	v_lshlrev_b32_e32 v156, 4, v1
	v_cndmask_b32_e64 v173, 0, 1.0, vcc
	v_cmp_eq_u32_e32 vcc, 15, v152
	v_writelane_b32 v248, s1, 15
	v_cmp_gt_u32_e64 s[0:1], 4, v152
	v_cndmask_b32_e64 v174, 0, 1.0, vcc
	v_cmp_eq_u32_e32 vcc, 16, v152
	v_writelane_b32 v248, s0, 16
	v_lshlrev_b32_e32 v158, 3, v1
	v_cndmask_b32_e64 v175, 0, 1.0, vcc
	v_cmp_eq_u32_e32 vcc, 17, v152
	v_writelane_b32 v248, s1, 17
	v_cmp_gt_u32_e64 s[0:1], 8, v152
	v_cndmask_b32_e64 v176, 0, 1.0, vcc
	v_cmp_eq_u32_e32 vcc, 18, v152
	v_writelane_b32 v248, s0, 18
	v_lshlrev_b32_e32 v4, 10, v1
	v_cndmask_b32_e64 v177, 0, 1.0, vcc
	v_cmp_eq_u32_e32 vcc, 19, v152
	v_writelane_b32 v248, s1, 19
	v_cmp_gt_u32_e64 s[0:1], 16, v152
	v_cndmask_b32_e64 v178, 0, 1.0, vcc
	v_cmp_eq_u32_e32 vcc, 20, v152
	v_writelane_b32 v248, s0, 20
	v_lshrrev_b32_e32 v1, 1, v184
	v_cndmask_b32_e64 v179, 0, 1.0, vcc
	v_cmp_eq_u32_e32 vcc, 21, v152
	v_writelane_b32 v248, s1, 21
	v_cmp_gt_u32_e64 s[0:1], 32, v152
	v_cndmask_b32_e64 v180, 0, 1.0, vcc
	v_cmp_eq_u32_e32 vcc, 22, v152
	v_writelane_b32 v248, s0, 22
	v_and_b32_e32 v132, 0x1c0, v1
	v_cndmask_b32_e64 v181, 0, 1.0, vcc
	v_cmp_eq_u32_e32 vcc, 23, v152
	v_mov_b32_e32 v133, 0
	v_lshrrev_b32_e32 v1, 4, v184
	v_cndmask_b32_e64 v182, 0, 1.0, vcc
	v_cmp_eq_u32_e32 vcc, 24, v152
	v_writelane_b32 v248, s1, 23
	v_cmp_ne_u32_e64 s[0:1], 0, v3
	v_cndmask_b32_e64 v183, 0, 1.0, vcc
	v_cmp_eq_u32_e32 vcc, 25, v152
	s_add_i32 s37, 0, 0x1a500
	v_and_b32_e32 v2, 4, v1
	v_cndmask_b32_e64 v185, 0, 1.0, vcc
	v_cmp_eq_u32_e32 vcc, 26, v152
	v_writelane_b32 v248, s0, 24
	v_mov_b32_e32 v1, v133
	v_cndmask_b32_e64 v186, 0, 1.0, vcc
	v_cmp_eq_u32_e32 vcc, 27, v152
	v_add_u32_e32 v154, s37, v0
	v_writelane_b32 v248, s1, 25
	v_cndmask_b32_e64 v187, 0, 1.0, vcc
	v_cmp_eq_u32_e32 vcc, 28, v152
	v_lshl_add_u64 v[0:1], s[50:51], 0, v[0:1]
	s_mov_b64 s[0:1], 0xd0e8800
	v_cndmask_b32_e64 v188, 0, 1.0, vcc
	v_cmp_eq_u32_e32 vcc, 29, v152
	v_lshl_add_u64 v[136:137], v[0:1], 0, s[0:1]
	v_lshl_add_u32 v0, v184, 2, 0
	v_cndmask_b32_e64 v189, 0, 1.0, vcc
	v_cmp_eq_u32_e32 vcc, 30, v152
	v_add_u32_e32 v224, 0x1a600, v0
	s_add_u32 s31, s50, 0xbee8800
	v_cndmask_b32_e64 v190, 0, 1.0, vcc
	v_cmp_eq_u32_e32 vcc, 31, v152
	v_mbcnt_lo_u32_b32 v0, -1, 0
	v_cmp_gt_u32_e64 s[2:3], 64, v184
	v_cndmask_b32_e64 v191, 0, 1.0, vcc
	v_cmp_eq_u32_e32 vcc, 32, v152
	s_mov_b32 s41, 0
	v_lshlrev_b32_e32 v155, 4, v3
	v_cndmask_b32_e64 v192, 0, 1.0, vcc
	v_cmp_eq_u32_e32 vcc, 33, v152
	v_lshl_add_u64 v[134:135], s[48:49], 0, v[132:133]
	v_and_b32_e32 v159, 0x7f, v184
	v_cndmask_b32_e64 v193, 0, 1.0, vcc
	v_cmp_eq_u32_e32 vcc, 34, v152
	v_cmp_lt_u32_e64 s[20:21], 1, v3
	v_cmp_eq_u32_e64 s[22:23], 3, v3
	v_cndmask_b32_e64 v194, 0, 1.0, vcc
	v_cmp_eq_u32_e32 vcc, 35, v152
	s_addc_u32 s35, s51, 0
	s_mov_b32 s15, -1
	v_cndmask_b32_e64 v195, 0, 1.0, vcc
	v_cmp_eq_u32_e32 vcc, 36, v152
	v_mov_b32_e32 v225, 0x3ecc95a3
	s_movk_i32 s38, 0x1a00
	v_cndmask_b32_e64 v196, 0, 1.0, vcc
	v_cmp_eq_u32_e32 vcc, 37, v152
	s_mov_b64 s[42:43], 0x3000a00
	s_mov_b32 s8, 0x3000000
	v_cndmask_b32_e64 v197, 0, 1.0, vcc
	v_cmp_eq_u32_e32 vcc, 38, v152
	s_movk_i32 s9, 0x1800
	s_movk_i32 s10, 0x110
	v_cndmask_b32_e64 v198, 0, 1.0, vcc
	v_cmp_eq_u32_e32 vcc, 39, v152
	s_mov_b32 s11, 0x800000
	s_mov_b64 s[46:47], 0x3000e00
	v_cndmask_b32_e64 v199, 0, 1.0, vcc
	v_cmp_eq_u32_e32 vcc, 40, v152
	s_mov_b64 s[66:67], 0x3001200
	s_mov_b32 s12, 0x3001000
	v_cndmask_b32_e64 v200, 0, 1.0, vcc
	v_cmp_eq_u32_e32 vcc, 41, v152
	s_add_i32 s13, 0, 0x11800
	v_lshlrev_b32_e32 v226, 1, v4
	v_cndmask_b32_e64 v201, 0, 1.0, vcc
	v_cmp_eq_u32_e32 vcc, 42, v152
	v_lshlrev_b32_e32 v138, 1, v2
	v_mov_b32_e32 v140, 0x3f317218
	v_cndmask_b32_e64 v202, 0, 1.0, vcc
	v_cmp_eq_u32_e32 vcc, 43, v152
	v_mov_b32_e32 v227, 0x7f800000
	v_mov_b32_e32 v228, 0x7fc00000
	v_cndmask_b32_e64 v203, 0, 1.0, vcc
	v_cmp_eq_u32_e32 vcc, 44, v152
	v_mov_b32_e32 v229, 0xff800000
	v_mbcnt_hi_u32_b32 v230, -1, v0
	v_cndmask_b32_e64 v204, 0, 1.0, vcc
	v_cmp_eq_u32_e32 vcc, 45, v152
	s_mov_b32 s30, s33
	s_cmpk_lt_i32 s33, 0x80
	s_cbranch_scc0 .Ldn_ord0
	s_bitcmp1_b32 s33, 0
	s_cbranch_scc0 .Ldn_ord0
	s_addk_i32 s30, 0x400

; __device__ __forceinline__ void dn_prep(const Params& p, LAS unsigned char* lds) {
;     ...
;     for (int ci = blockIdx.x; ci < NCH; ci += gridDim.x) {
;         const bool samp = ci >= 1024;
;         if ((ci & 3) != hb) { hb = ci & 3;
.LBB0_190:
	s_or_b64 exec, exec, s[26:27]
	s_waitcnt lgkmcnt(0)
	s_barrier
	s_bitcmp1_b32 s33, 0
	s_cbranch_scc0 .Ldn_ord3
	s_cmpk_lt_i32 s30, 0x400
	s_cbranch_scc1 .Ldn_ord1
	s_addk_i32 s30, 0xfc00
	s_branch .Ldn_ord2
.Ldn_ord1:
	s_add_i32 s30, s30, s86
	s_cmpk_gt_i32 s30, 0x3ff
	s_cbranch_scc1 .LBB0_384
	s_branch .Ldn_ord2
.Ldn_ord3:
	s_add_i32 s30, s30, s86
	s_cmpk_gt_i32 s30, 0x47f
	s_cbranch_scc1 .LBB0_384
